# sc1 write-through stores in in-proj and mlp-out epilogues plus dilmerge (phases that end at a grid barrier)
# speedup vs baseline: 1.0194x; 1.0043x over previous
.LBB0_1051:
	s_waitcnt lgkmcnt(0)
	v_lshl_add_u64 v[2:3], s[18:19], 0, v[12:13]
	v_add_co_u32_e32 v4, vcc, 0x2a100000, v2
	s_waitcnt vmcnt(19)
	v_lshl_add_u64 v[18:19], s[18:19], 0, v[10:11]
	v_addc_co_u32_e32 v5, vcc, 0, v3, vcc
	global_load_dword v0, v[4:5], off
	v_add_co_u32_e32 v4, vcc, 0x2a120000, v2
	s_mov_b32 s1, 0x28900000
	s_nop 0
	v_addc_co_u32_e32 v5, vcc, 0, v3, vcc
	v_add_co_u32_e32 v2, vcc, 0x2a140000, v2
	global_load_dword v4, v[4:5], off
	s_nop 0
	v_addc_co_u32_e32 v3, vcc, 0, v3, vcc
	global_load_dword v2, v[2:3], off
	v_add_co_u32_e32 v30, vcc, 0x28900000, v18
	s_nop 1
	v_addc_co_u32_e32 v31, vcc, 0, v19, vcc
	global_load_dwordx4 v[132:135], v[30:31], off
	v_add_co_u32_e32 v32, vcc, 0x29100000, v18
	s_nop 1
	v_addc_co_u32_e32 v33, vcc, 0, v19, vcc
	global_load_dwordx4 v[136:139], v[32:33], off
	v_add_co_u32_e32 v140, vcc, 0x29900000, v18
	s_nop 1
	v_addc_co_u32_e32 v141, vcc, 0, v19, vcc
	global_load_dwordx4 v[36:39], v[140:141], off
	v_add_u32_e32 v6, s12, v6
	v_lshl_add_u64 v[10:11], v[10:11], 0, s[20:21]
	v_lshl_add_u64 v[12:13], v[12:13], 0, s[22:23]
	s_waitcnt vmcnt(3)
	v_max3_f32 v3, v0, v4, v2
	v_sub_f32_e32 v0, v0, v3
	v_mul_f32_e32 v0, 0x3fb8aa3b, v0
	v_sub_f32_e32 v4, v4, v3
	v_exp_f32_e32 v0, v0
	v_mul_f32_e32 v4, 0x3fb8aa3b, v4
	v_sub_f32_e32 v2, v2, v3
	v_exp_f32_e32 v7, v4
	v_mul_f32_e32 v2, 0x3fb8aa3b, v2
	v_exp_f32_e32 v23, v2
	v_add_f32_e32 v5, 0, v0
	v_add_f32_e32 v4, v7, v5
	v_add_f32_e32 v2, v23, v4
	v_div_scale_f32 v3, s[4:5], v2, v2, 1.0
	v_rcp_f32_e32 v4, v3
	s_nop 0
	v_fma_f32 v5, -v3, v4, 1.0
	v_fmac_f32_e32 v4, v5, v4
	v_div_scale_f32 v5, vcc, 1.0, v2, 1.0
	v_mul_f32_e32 v14, v5, v4
	v_fma_f32 v15, -v3, v14, v5
	v_fmac_f32_e32 v14, v15, v4
	v_fma_f32 v3, -v3, v14, v5
	v_div_fmas_f32 v3, v3, v4, v14
	v_div_fixup_f32 v24, v3, v2, 1.0
	v_add_co_u32_e32 v2, vcc, s1, v18
	s_mov_b32 s1, 0x29100000
	s_nop 0
	v_addc_co_u32_e32 v3, vcc, 0, v19, vcc
	v_add_co_u32_e32 v14, vcc, s1, v18
	s_mov_b32 s1, 0x29900000
	s_nop 0
	v_addc_co_u32_e32 v15, vcc, 0, v19, vcc
	s_waitcnt vmcnt(2)
	v_mov_b32_e32 v2, v132
	v_mov_b32_e32 v3, v133
	v_mov_b32_e32 v4, v134
	v_mov_b32_e32 v5, v135
	v_add_co_u32_e32 v18, vcc, s1, v18
	s_waitcnt vmcnt(1)
	v_mov_b32_e32 v14, v136
	v_mov_b32_e32 v15, v137
	v_mov_b32_e32 v16, v138
	v_mov_b32_e32 v17, v139
	s_nop 0
	v_addc_co_u32_e32 v19, vcc, 0, v19, vcc
	s_waitcnt vmcnt(0)
	v_mov_b32_e32 v18, v36
	v_mov_b32_e32 v19, v37
	v_mov_b32_e32 v20, v38
	v_mov_b32_e32 v21, v39
	v_mul_f32_e32 v0, v0, v24
	v_mul_f32_e32 v22, v7, v24
	v_mul_f32_e32 v24, v23, v24
	s_movk_i32 s1, 0x1fff
	v_cmp_lt_i32_e32 vcc, s1, v6
	s_or_b64 s[30:31], vcc, s[30:31]
	s_waitcnt vmcnt(2)
	v_lshlrev_b32_e32 v27, 16, v3
	v_lshlrev_b32_e32 v26, 16, v2
	v_and_b32_e32 v3, 0xffff0000, v3
	v_and_b32_e32 v2, 0xffff0000, v2
	v_pk_fma_f32 v[2:3], v[0:1], v[2:3], 0 op_sel_hi:[0,1,0]
	s_waitcnt vmcnt(1)
	v_lshlrev_b32_e32 v29, 16, v15
	v_lshlrev_b32_e32 v28, 16, v14
	v_and_b32_e32 v15, 0xffff0000, v15
	v_and_b32_e32 v14, 0xffff0000, v14
	v_pk_fma_f32 v[26:27], v[0:1], v[26:27], 0 op_sel_hi:[0,1,0]
	v_pk_fma_f32 v[2:3], v[22:23], v[14:15], v[2:3] op_sel_hi:[0,1,1]
	s_waitcnt vmcnt(0)
	v_lshlrev_b32_e32 v15, 16, v19
	v_lshlrev_b32_e32 v14, 16, v18
	v_and_b32_e32 v19, 0xffff0000, v19
	v_and_b32_e32 v18, 0xffff0000, v18
	v_pk_fma_f32 v[26:27], v[22:23], v[28:29], v[26:27] op_sel_hi:[0,1,1]
	v_pk_fma_f32 v[2:3], v[24:25], v[18:19], v[2:3] op_sel_hi:[0,1,1]
	v_lshlrev_b32_e32 v19, 16, v5
	v_lshlrev_b32_e32 v18, 16, v4
	v_and_b32_e32 v5, 0xffff0000, v5
	v_and_b32_e32 v4, 0xffff0000, v4
	v_pk_fma_f32 v[14:15], v[24:25], v[14:15], v[26:27] op_sel_hi:[0,1,1]
	v_pk_fma_f32 v[18:19], v[0:1], v[18:19], 0 op_sel_hi:[0,1,0]
	v_pk_fma_f32 v[4:5], v[0:1], v[4:5], 0 op_sel_hi:[0,1,0]
	v_lshlrev_b32_e32 v27, 16, v17
	v_lshlrev_b32_e32 v26, 16, v16
	v_and_b32_e32 v17, 0xffff0000, v17
	v_and_b32_e32 v16, 0xffff0000, v16
	v_pk_fma_f32 v[18:19], v[22:23], v[26:27], v[18:19] op_sel_hi:[0,1,1]
	v_pk_fma_f32 v[4:5], v[22:23], v[16:17], v[4:5] op_sel_hi:[0,1,1]
	v_lshlrev_b32_e32 v17, 16, v21
	v_lshlrev_b32_e32 v16, 16, v20
	v_pk_fma_f32 v[16:17], v[24:25], v[16:17], v[18:19] op_sel_hi:[0,1,1]
	v_and_b32_e32 v19, 0xffff0000, v21
	v_and_b32_e32 v18, 0xffff0000, v20
	v_pk_fma_f32 v[4:5], v[24:25], v[18:19], v[4:5] op_sel_hi:[0,1,1]
	v_bfe_u32 v0, v5, 16, 1
	v_bfe_u32 v7, v4, 16, 1
	v_bfe_u32 v18, v3, 16, 1
	v_bfe_u32 v19, v2, 16, 1
	v_add3_u32 v2, v2, v19, s92
	v_add3_u32 v3, v3, v18, s92
	v_add3_u32 v4, v4, v7, s92
	v_add3_u32 v0, v5, v0, s92
	v_bfe_u32 v5, v14, 16, 1
	v_bfe_u32 v7, v15, 16, 1
	v_bfe_u32 v18, v16, 16, 1
	v_bfe_u32 v19, v17, 16, 1
	v_add3_u32 v17, v17, v19, s92
	v_add3_u32 v16, v16, v18, s92
	v_add3_u32 v7, v15, v7, s92
	v_add3_u32 v5, v14, v5, s92
	v_lshrrev_b32_e32 v14, 16, v5
	v_lshrrev_b32_e32 v7, 16, v7
	v_lshrrev_b32_e32 v15, 16, v16
	v_lshrrev_b32_e32 v5, 16, v17
	v_and_or_b32 v5, v0, s97, v5
	v_and_or_b32 v4, v4, s97, v15
	v_and_or_b32 v3, v3, s97, v7
	v_and_or_b32 v2, v2, s97, v14
	v_lshl_add_u64 v[14:15], s[18:19], 0, v[8:9]
	v_lshl_add_u64 v[8:9], v[8:9], 0, s[14:15]
	global_store_dwordx4 v[14:15], v[2:5], off sc1
	s_andn2_b64 exec, exec, s[30:31]
	s_cbranch_execnz .LBB0_1051

.LBB0_1425:
	v_lshl_add_u32 v200, s58, 8, v231
	v_lshl_or_b32 v196, s56, 8, v233
	v_ashrrev_i32_e32 v197, 31, v196
	v_ashrrev_i32_e32 v201, 31, v200
	v_lshl_add_u64 v[198:199], v[196:197], 2, s[18:19]
	v_lshlrev_b64 v[126:127], 13, v[200:201]
	v_lshl_add_u64 v[126:127], v[198:199], 0, v[126:127]
	global_load_dwordx4 v[186:189], v[126:127], off
	global_load_dwordx4 v[218:221], v[126:127], off offset:64
	global_load_dwordx4 v[182:185], v[126:127], off offset:512
	global_load_dwordx4 v[178:181], v[126:127], off offset:576
	v_or_b32_e32 v206, 16, v200
	v_ashrrev_i32_e32 v207, 31, v206
	v_lshlrev_b64 v[126:127], 13, v[206:207]
	v_or_b32_e32 v204, 32, v200
	v_lshl_add_u64 v[126:127], v[198:199], 0, v[126:127]
	v_ashrrev_i32_e32 v205, 31, v204
	global_load_dwordx4 v[174:177], v[126:127], off
	global_load_dwordx4 v[170:173], v[126:127], off offset:64
	global_load_dwordx4 v[166:169], v[126:127], off offset:512
	global_load_dwordx4 v[162:165], v[126:127], off offset:576
	v_lshlrev_b64 v[126:127], 13, v[204:205]
	v_or_b32_e32 v202, 48, v200
	v_lshl_add_u64 v[126:127], v[198:199], 0, v[126:127]
	v_ashrrev_i32_e32 v203, 31, v202
	global_load_dwordx4 v[158:161], v[126:127], off
	global_load_dwordx4 v[154:157], v[126:127], off offset:64
	global_load_dwordx4 v[146:149], v[126:127], off offset:512
	global_load_dwordx4 v[134:137], v[126:127], off offset:576
	v_lshlrev_b64 v[126:127], 13, v[202:203]
	v_lshl_add_u64 v[126:127], v[198:199], 0, v[126:127]
	global_load_dwordx4 v[150:153], v[126:127], off
	global_load_dwordx4 v[138:141], v[126:127], off offset:64
	global_load_dwordx4 v[130:133], v[126:127], off offset:512
	s_nop 0
	global_load_dwordx4 v[126:129], v[126:127], off offset:576
	v_lshlrev_b64 v[208:209], 11, v[200:201]
	v_lshl_add_u64 v[208:209], v[208:209], 0, v[196:197]
	s_lshl_b32 s56, s56, 2
	s_ashr_i32 s57, s56, 31
	s_waitcnt vmcnt(0)
	v_pk_add_f32 v[144:145], v[144:145], v[188:189]
	v_pk_add_f32 v[142:143], v[142:143], v[186:187]
	v_lshl_add_u64 v[186:187], v[208:209], 2, s[30:31]
	global_store_dwordx4 v[186:187], v[142:145], off sc1
	v_mul_f32_e32 v186, v143, v143
	v_mul_f32_e32 v187, v145, v145
	v_fmac_f32_e32 v186, v142, v142
	v_fmac_f32_e32 v187, v144, v144
	v_cvt_pk_bf16_f32 v142, v142, v143
	v_cvt_pk_bf16_f32 v143, v144, v145
	v_lshl_add_u64 v[144:145], v[208:209], 1, s[36:37]
	global_store_dwordx2 v[144:145], v[142:143], off
	v_or_b32_e32 v142, 16, v208
	v_mov_b32_e32 v143, v209
	v_pk_add_f32 v[124:125], v[124:125], v[220:221]
	v_pk_add_f32 v[122:123], v[122:123], v[218:219]
	v_lshl_add_u64 v[144:145], v[142:143], 2, s[30:31]
	global_store_dwordx4 v[144:145], v[122:125], off sc1
	v_mul_f32_e32 v144, v123, v123
	v_mul_f32_e32 v145, v125, v125
	v_fmac_f32_e32 v144, v122, v122
	v_fmac_f32_e32 v145, v124, v124
	v_cvt_pk_bf16_f32 v122, v122, v123
	v_cvt_pk_bf16_f32 v123, v124, v125
	v_lshl_add_u64 v[124:125], v[142:143], 1, s[36:37]
	global_store_dwordx2 v[124:125], v[122:123], off
	v_or_b32_e32 v122, 0x80, v208
	v_mov_b32_e32 v123, v209
	v_pk_add_f32 v[120:121], v[120:121], v[184:185]
	v_pk_add_f32 v[118:119], v[118:119], v[182:183]
	v_lshl_add_u64 v[124:125], v[122:123], 2, s[30:31]
	global_store_dwordx4 v[124:125], v[118:121], off sc1
	v_mul_f32_e32 v124, v119, v119
	v_mul_f32_e32 v125, v121, v121
	v_fmac_f32_e32 v124, v118, v118
	v_fmac_f32_e32 v125, v120, v120
	v_cvt_pk_bf16_f32 v118, v118, v119
	v_cvt_pk_bf16_f32 v119, v120, v121
	v_lshl_add_u64 v[120:121], v[122:123], 1, s[36:37]
	v_or_b32_e32 v208, 0x90, v208
	global_store_dwordx2 v[120:121], v[118:119], off
	v_pk_add_f32 v[116:117], v[116:117], v[180:181]
	v_pk_add_f32 v[114:115], v[114:115], v[178:179]
	v_lshl_add_u64 v[118:119], v[208:209], 2, s[30:31]
	global_store_dwordx4 v[118:119], v[114:117], off sc1
	v_mul_f32_e32 v118, v115, v115
	v_mul_f32_e32 v119, v117, v117
	v_fmac_f32_e32 v118, v114, v114
	v_fmac_f32_e32 v119, v116, v116
	v_cvt_pk_bf16_f32 v114, v114, v115
	v_cvt_pk_bf16_f32 v115, v116, v117
	v_lshl_add_u64 v[116:117], v[208:209], 1, s[36:37]
	v_add_f32_e32 v186, v186, v187
	v_add_f32_e32 v144, v144, v145
	global_store_dwordx2 v[116:117], v[114:115], off
	v_xor_b32_e32 v114, 16, v213
	v_add_f32_e32 v144, v186, v144
	v_add_f32_e32 v124, v124, v125
	v_cmp_lt_i32_e32 vcc, v114, v216
	v_add_f32_e32 v124, v144, v124
	v_add_f32_e32 v118, v118, v119
	v_cndmask_b32_e32 v114, v213, v114, vcc
	v_add_f32_e32 v118, v124, v118
	v_lshlrev_b32_e32 v142, 2, v114
	ds_bpermute_b32 v114, v142, v118
	v_xor_b32_e32 v115, 32, v213
	v_cmp_lt_i32_e32 vcc, v115, v216
	s_waitcnt lgkmcnt(0)
	v_add_f32_e32 v114, v118, v114
	v_cndmask_b32_e32 v115, v213, v115, vcc
	v_lshlrev_b32_e32 v143, 2, v115
	ds_bpermute_b32 v115, v143, v114
	s_and_saveexec_b64 s[4:5], s[40:41]
	s_cbranch_execz .LBB0_1427
	v_lshlrev_b64 v[116:117], 7, v[200:201]
	v_lshl_add_u64 v[116:117], s[44:45], 0, v[116:117]
	v_lshl_add_u64 v[116:117], s[56:57], 2, v[116:117]
	s_lshl_b32 s10, s23, 2
	v_lshl_add_u64 v[116:117], v[116:117], 0, s[10:11]
	s_waitcnt lgkmcnt(0)
	v_add_f32_e32 v114, v114, v115
	global_store_dword v[116:117], v114, off
.LBB0_1427:
	s_or_b64 exec, exec, s[4:5]
	s_waitcnt lgkmcnt(0)
	v_lshlrev_b64 v[114:115], 11, v[206:207]
	v_lshl_add_u64 v[114:115], v[114:115], 0, v[196:197]
	v_pk_add_f32 v[112:113], v[112:113], v[176:177]
	v_pk_add_f32 v[110:111], v[110:111], v[174:175]
	v_lshl_add_u64 v[116:117], v[114:115], 2, s[30:31]
	global_store_dwordx4 v[116:117], v[110:113], off sc1
	v_mul_f32_e32 v116, v111, v111
	v_mul_f32_e32 v117, v113, v113
	v_fmac_f32_e32 v116, v110, v110
	v_fmac_f32_e32 v117, v112, v112
	v_cvt_pk_bf16_f32 v110, v110, v111
	v_cvt_pk_bf16_f32 v111, v112, v113
	v_lshl_add_u64 v[112:113], v[114:115], 1, s[36:37]
	global_store_dwordx2 v[112:113], v[110:111], off
	v_or_b32_e32 v110, 16, v114
	v_mov_b32_e32 v111, v115
	v_pk_add_f32 v[108:109], v[108:109], v[172:173]
	v_pk_add_f32 v[106:107], v[106:107], v[170:171]
	v_lshl_add_u64 v[112:113], v[110:111], 2, s[30:31]
	global_store_dwordx4 v[112:113], v[106:109], off sc1
	v_mul_f32_e32 v112, v107, v107
	v_mul_f32_e32 v113, v109, v109
	v_fmac_f32_e32 v112, v106, v106
	v_fmac_f32_e32 v113, v108, v108
	v_cvt_pk_bf16_f32 v106, v106, v107
	v_cvt_pk_bf16_f32 v107, v108, v109
	v_lshl_add_u64 v[108:109], v[110:111], 1, s[36:37]
	global_store_dwordx2 v[108:109], v[106:107], off
	v_or_b32_e32 v106, 0x80, v114
	v_mov_b32_e32 v107, v115
	v_pk_add_f32 v[104:105], v[104:105], v[168:169]
	v_pk_add_f32 v[102:103], v[102:103], v[166:167]
	v_lshl_add_u64 v[108:109], v[106:107], 2, s[30:31]
	global_store_dwordx4 v[108:109], v[102:105], off sc1
	v_mul_f32_e32 v108, v103, v103
	v_mul_f32_e32 v109, v105, v105
	v_add_f32_e32 v116, v116, v117
	v_add_f32_e32 v112, v112, v113
	v_fmac_f32_e32 v108, v102, v102
	v_fmac_f32_e32 v109, v104, v104
	v_add_f32_e32 v112, v116, v112
	v_add_f32_e32 v108, v108, v109
	v_add_f32_e32 v110, v112, v108
	v_cvt_pk_bf16_f32 v108, v102, v103
	v_pk_add_f32 v[102:103], v[100:101], v[164:165]
	v_pk_add_f32 v[100:101], v[98:99], v[162:163]
	v_mul_f32_e32 v99, v103, v103
	v_mul_f32_e32 v98, v101, v101
	v_fmac_f32_e32 v98, v100, v100
	v_fmac_f32_e32 v99, v102, v102
	v_add_f32_e32 v98, v98, v99
	v_cvt_pk_bf16_f32 v109, v104, v105
	v_lshl_add_u64 v[104:105], v[106:107], 1, s[36:37]
	v_add_f32_e32 v106, v110, v98
	ds_bpermute_b32 v107, v142, v106
	v_or_b32_e32 v114, 0x90, v114
	v_lshl_add_u64 v[98:99], v[114:115], 2, s[30:31]
	global_store_dwordx2 v[104:105], v[108:109], off
	global_store_dwordx4 v[98:99], v[100:103], off sc1
	s_waitcnt lgkmcnt(0)
	v_add_f32_e32 v98, v106, v107
	ds_bpermute_b32 v99, v143, v98
	v_cvt_pk_bf16_f32 v100, v100, v101
	v_cvt_pk_bf16_f32 v101, v102, v103
	v_lshl_add_u64 v[102:103], v[114:115], 1, s[36:37]
	global_store_dwordx2 v[102:103], v[100:101], off
	s_and_saveexec_b64 s[4:5], s[40:41]
	s_cbranch_execz .LBB0_1429
	v_lshlrev_b64 v[100:101], 7, v[206:207]
	v_lshl_add_u64 v[100:101], s[44:45], 0, v[100:101]
	v_lshl_add_u64 v[100:101], s[56:57], 2, v[100:101]
	s_lshl_b32 s10, s23, 2
	v_lshl_add_u64 v[100:101], v[100:101], 0, s[10:11]
	s_waitcnt lgkmcnt(0)
	v_add_f32_e32 v98, v98, v99
	global_store_dword v[100:101], v98, off
.LBB0_1429:
	s_or_b64 exec, exec, s[4:5]
	s_waitcnt lgkmcnt(0)
	v_lshlrev_b64 v[98:99], 11, v[204:205]
	v_lshl_add_u64 v[98:99], v[98:99], 0, v[196:197]
	v_pk_add_f32 v[96:97], v[96:97], v[160:161]
	v_pk_add_f32 v[94:95], v[94:95], v[158:159]
	v_lshl_add_u64 v[100:101], v[98:99], 2, s[30:31]
	global_store_dwordx4 v[100:101], v[94:97], off sc1
	v_mul_f32_e32 v100, v95, v95
	v_mul_f32_e32 v101, v97, v97
	v_fmac_f32_e32 v100, v94, v94
	v_fmac_f32_e32 v101, v96, v96
	v_cvt_pk_bf16_f32 v94, v94, v95
	v_cvt_pk_bf16_f32 v95, v96, v97
	v_lshl_add_u64 v[96:97], v[98:99], 1, s[36:37]
	global_store_dwordx2 v[96:97], v[94:95], off
	v_or_b32_e32 v94, 16, v98
	v_mov_b32_e32 v95, v99
	v_pk_add_f32 v[92:93], v[92:93], v[156:157]
	v_pk_add_f32 v[90:91], v[90:91], v[154:155]
	v_lshl_add_u64 v[96:97], v[94:95], 2, s[30:31]
	global_store_dwordx4 v[96:97], v[90:93], off sc1
	v_mul_f32_e32 v96, v91, v91
	v_mul_f32_e32 v97, v93, v93
	v_fmac_f32_e32 v96, v90, v90
	v_fmac_f32_e32 v97, v92, v92
	v_cvt_pk_bf16_f32 v90, v90, v91
	v_cvt_pk_bf16_f32 v91, v92, v93
	v_lshl_add_u64 v[92:93], v[94:95], 1, s[36:37]
	global_store_dwordx2 v[92:93], v[90:91], off
	v_or_b32_e32 v90, 0x80, v98
	v_mov_b32_e32 v91, v99
	v_pk_add_f32 v[88:89], v[88:89], v[148:149]
	v_pk_add_f32 v[86:87], v[86:87], v[146:147]
	v_lshl_add_u64 v[92:93], v[90:91], 2, s[30:31]
	global_store_dwordx4 v[92:93], v[86:89], off sc1
	v_mul_f32_e32 v92, v87, v87
	v_mul_f32_e32 v93, v89, v89
	v_add_f32_e32 v100, v100, v101
	v_add_f32_e32 v96, v96, v97
	v_fmac_f32_e32 v92, v86, v86
	v_fmac_f32_e32 v93, v88, v88
	v_add_f32_e32 v96, v100, v96
	v_add_f32_e32 v92, v92, v93
	v_add_f32_e32 v94, v96, v92
	v_cvt_pk_bf16_f32 v92, v86, v87
	v_pk_add_f32 v[86:87], v[84:85], v[136:137]
	v_pk_add_f32 v[84:85], v[82:83], v[134:135]
	v_mul_f32_e32 v83, v87, v87
	v_mul_f32_e32 v82, v85, v85
	v_fmac_f32_e32 v82, v84, v84
	v_fmac_f32_e32 v83, v86, v86
	v_add_f32_e32 v82, v82, v83
	v_cvt_pk_bf16_f32 v93, v88, v89
	v_lshl_add_u64 v[88:89], v[90:91], 1, s[36:37]
	v_add_f32_e32 v90, v94, v82
	ds_bpermute_b32 v91, v142, v90
	v_or_b32_e32 v98, 0x90, v98
	v_lshl_add_u64 v[82:83], v[98:99], 2, s[30:31]
	global_store_dwordx2 v[88:89], v[92:93], off
	global_store_dwordx4 v[82:83], v[84:87], off sc1
	s_waitcnt lgkmcnt(0)
	v_add_f32_e32 v82, v90, v91
	ds_bpermute_b32 v83, v143, v82
	v_cvt_pk_bf16_f32 v84, v84, v85
	v_cvt_pk_bf16_f32 v85, v86, v87
	v_lshl_add_u64 v[86:87], v[98:99], 1, s[36:37]
	global_store_dwordx2 v[86:87], v[84:85], off
	s_and_saveexec_b64 s[4:5], s[40:41]
	s_cbranch_execz .LBB0_1431
	v_lshlrev_b64 v[84:85], 7, v[204:205]
	v_lshl_add_u64 v[84:85], s[44:45], 0, v[84:85]
	v_lshl_add_u64 v[84:85], s[56:57], 2, v[84:85]
	s_lshl_b32 s10, s23, 2
	v_lshl_add_u64 v[84:85], v[84:85], 0, s[10:11]
	s_waitcnt lgkmcnt(0)
	v_add_f32_e32 v82, v82, v83
	global_store_dword v[84:85], v82, off
.LBB0_1431:
	s_or_b64 exec, exec, s[4:5]
	s_waitcnt lgkmcnt(0)
	v_lshlrev_b64 v[82:83], 11, v[202:203]
	v_lshl_add_u64 v[82:83], v[82:83], 0, v[196:197]
	v_pk_add_f32 v[80:81], v[80:81], v[152:153]
	v_pk_add_f32 v[78:79], v[78:79], v[150:151]
	v_lshl_add_u64 v[84:85], v[82:83], 2, s[30:31]
	global_store_dwordx4 v[84:85], v[78:81], off sc1
	v_mul_f32_e32 v84, v79, v79
	v_mul_f32_e32 v85, v81, v81
	v_fmac_f32_e32 v84, v78, v78
	v_fmac_f32_e32 v85, v80, v80
	v_cvt_pk_bf16_f32 v78, v78, v79
	v_cvt_pk_bf16_f32 v79, v80, v81
	v_lshl_add_u64 v[80:81], v[82:83], 1, s[36:37]
	global_store_dwordx2 v[80:81], v[78:79], off
	v_or_b32_e32 v78, 16, v82
	v_mov_b32_e32 v79, v83
	v_pk_add_f32 v[76:77], v[76:77], v[140:141]
	v_pk_add_f32 v[74:75], v[74:75], v[138:139]
	v_lshl_add_u64 v[80:81], v[78:79], 2, s[30:31]
	global_store_dwordx4 v[80:81], v[74:77], off sc1
	v_mul_f32_e32 v80, v75, v75
	v_mul_f32_e32 v81, v77, v77
	v_fmac_f32_e32 v80, v74, v74
	v_fmac_f32_e32 v81, v76, v76
	v_cvt_pk_bf16_f32 v74, v74, v75
	v_cvt_pk_bf16_f32 v75, v76, v77
	v_lshl_add_u64 v[76:77], v[78:79], 1, s[36:37]
	global_store_dwordx2 v[76:77], v[74:75], off
	v_or_b32_e32 v74, 0x80, v82
	v_mov_b32_e32 v75, v83
	v_pk_add_f32 v[72:73], v[72:73], v[132:133]
	v_pk_add_f32 v[70:71], v[70:71], v[130:131]
	v_lshl_add_u64 v[76:77], v[74:75], 2, s[30:31]
	global_store_dwordx4 v[76:77], v[70:73], off sc1
	v_mul_f32_e32 v76, v71, v71
	v_mul_f32_e32 v77, v73, v73
	v_add_f32_e32 v84, v84, v85
	v_add_f32_e32 v80, v80, v81
	v_fmac_f32_e32 v76, v70, v70
	v_fmac_f32_e32 v77, v72, v72
	v_add_f32_e32 v80, v84, v80
	v_add_f32_e32 v76, v76, v77
	v_add_f32_e32 v78, v80, v76
	v_cvt_pk_bf16_f32 v76, v70, v71
	v_pk_add_f32 v[70:71], v[68:69], v[128:129]
	v_pk_add_f32 v[68:69], v[66:67], v[126:127]
	v_mul_f32_e32 v67, v71, v71
	v_mul_f32_e32 v66, v69, v69
	v_fmac_f32_e32 v66, v68, v68
	v_fmac_f32_e32 v67, v70, v70
	v_add_f32_e32 v66, v66, v67
	v_cvt_pk_bf16_f32 v77, v72, v73
	v_lshl_add_u64 v[72:73], v[74:75], 1, s[36:37]
	v_add_f32_e32 v74, v78, v66
	ds_bpermute_b32 v75, v142, v74
	v_or_b32_e32 v82, 0x90, v82
	v_lshl_add_u64 v[66:67], v[82:83], 2, s[30:31]
	global_store_dwordx2 v[72:73], v[76:77], off
	global_store_dwordx4 v[66:67], v[68:71], off sc1
	s_waitcnt lgkmcnt(0)
	v_add_f32_e32 v66, v74, v75
	ds_bpermute_b32 v67, v143, v66
	v_cvt_pk_bf16_f32 v68, v68, v69
	v_cvt_pk_bf16_f32 v69, v70, v71
	v_lshl_add_u64 v[70:71], v[82:83], 1, s[36:37]
	global_store_dwordx2 v[70:71], v[68:69], off
	s_and_saveexec_b64 s[4:5], s[40:41]
	s_cbranch_execz .LBB0_1433
	v_lshlrev_b64 v[68:69], 7, v[202:203]
	v_lshl_add_u64 v[68:69], s[44:45], 0, v[68:69]
	v_lshl_add_u64 v[68:69], s[56:57], 2, v[68:69]
	s_lshl_b32 s10, s23, 2
	v_lshl_add_u64 v[68:69], v[68:69], 0, s[10:11]
	s_waitcnt lgkmcnt(0)
	v_add_f32_e32 v66, v66, v67
	global_store_dword v[68:69], v66, off
.LBB0_1433:
	s_or_b64 exec, exec, s[4:5]
	v_add_u32_e32 v128, 0x80, v200
	v_ashrrev_i32_e32 v129, 31, v128
	s_waitcnt lgkmcnt(0)
	v_lshlrev_b64 v[66:67], 13, v[128:129]
	v_lshl_add_u64 v[66:67], v[198:199], 0, v[66:67]
	global_load_dwordx4 v[132:135], v[66:67], off
	global_load_dwordx4 v[136:139], v[66:67], off offset:64
	global_load_dwordx4 v[118:121], v[66:67], off offset:512
	global_load_dwordx4 v[114:117], v[66:67], off offset:576
	v_add_u32_e32 v126, 0x90, v200
	v_ashrrev_i32_e32 v127, 31, v126
	v_lshlrev_b64 v[66:67], 13, v[126:127]
	v_add_u32_e32 v124, 0xa0, v200
	v_lshl_add_u64 v[66:67], v[198:199], 0, v[66:67]
	v_ashrrev_i32_e32 v125, 31, v124
	global_load_dwordx4 v[110:113], v[66:67], off
	global_load_dwordx4 v[106:109], v[66:67], off offset:64
	global_load_dwordx4 v[102:105], v[66:67], off offset:512
	global_load_dwordx4 v[98:101], v[66:67], off offset:576
	v_lshlrev_b64 v[66:67], 13, v[124:125]
	v_add_u32_e32 v122, 0xb0, v200
	v_lshl_add_u64 v[66:67], v[198:199], 0, v[66:67]
	v_ashrrev_i32_e32 v123, 31, v122
	global_load_dwordx4 v[94:97], v[66:67], off
	global_load_dwordx4 v[90:93], v[66:67], off offset:64
	global_load_dwordx4 v[82:85], v[66:67], off offset:512
	global_load_dwordx4 v[74:77], v[66:67], off offset:576
	v_lshlrev_b64 v[66:67], 13, v[122:123]
	v_lshl_add_u64 v[66:67], v[198:199], 0, v[66:67]
	global_load_dwordx4 v[86:89], v[66:67], off
	global_load_dwordx4 v[78:81], v[66:67], off offset:64
	global_load_dwordx4 v[70:73], v[66:67], off offset:512
	s_nop 0
	global_load_dwordx4 v[66:69], v[66:67], off offset:576
	v_lshlrev_b64 v[130:131], 11, v[128:129]
	v_lshl_add_u64 v[130:131], v[130:131], 0, v[196:197]
	s_waitcnt vmcnt(15)
	v_pk_add_f32 v[64:65], v[64:65], v[134:135]
	v_pk_add_f32 v[62:63], v[62:63], v[132:133]
	v_lshl_add_u64 v[132:133], v[130:131], 2, s[30:31]
	global_store_dwordx4 v[132:133], v[62:65], off sc1
	v_mul_f32_e32 v132, v63, v63
	v_mul_f32_e32 v133, v65, v65
	v_fmac_f32_e32 v132, v62, v62
	v_fmac_f32_e32 v133, v64, v64
	v_cvt_pk_bf16_f32 v62, v62, v63
	v_cvt_pk_bf16_f32 v63, v64, v65
	v_lshl_add_u64 v[64:65], v[130:131], 1, s[36:37]
	global_store_dwordx2 v[64:65], v[62:63], off
	v_or_b32_e32 v62, 16, v130
	v_mov_b32_e32 v63, v131
	s_waitcnt vmcnt(16)
	v_pk_add_f32 v[60:61], v[60:61], v[138:139]
	v_pk_add_f32 v[58:59], v[58:59], v[136:137]
	v_lshl_add_u64 v[64:65], v[62:63], 2, s[30:31]
	global_store_dwordx4 v[64:65], v[58:61], off sc1
	v_mul_f32_e32 v64, v59, v59
	v_mul_f32_e32 v65, v61, v61
	v_fmac_f32_e32 v64, v58, v58
	v_fmac_f32_e32 v65, v60, v60
	v_cvt_pk_bf16_f32 v58, v58, v59
	v_cvt_pk_bf16_f32 v59, v60, v61
	v_lshl_add_u64 v[60:61], v[62:63], 1, s[36:37]
	global_store_dwordx2 v[60:61], v[58:59], off
	v_or_b32_e32 v58, 0x80, v130
	v_mov_b32_e32 v59, v131
	s_waitcnt vmcnt(17)
	v_pk_add_f32 v[56:57], v[56:57], v[120:121]
	v_pk_add_f32 v[54:55], v[54:55], v[118:119]
	v_lshl_add_u64 v[60:61], v[58:59], 2, s[30:31]
	global_store_dwordx4 v[60:61], v[54:57], off sc1
	v_mul_f32_e32 v60, v55, v55
	v_mul_f32_e32 v61, v57, v57
	v_fmac_f32_e32 v60, v54, v54
	v_fmac_f32_e32 v61, v56, v56
	v_cvt_pk_bf16_f32 v54, v54, v55
	v_cvt_pk_bf16_f32 v55, v56, v57
	v_lshl_add_u64 v[56:57], v[58:59], 1, s[36:37]
	v_or_b32_e32 v130, 0x90, v130
	global_store_dwordx2 v[56:57], v[54:55], off
	s_waitcnt vmcnt(18)
	v_pk_add_f32 v[52:53], v[52:53], v[116:117]
	v_pk_add_f32 v[50:51], v[50:51], v[114:115]
	v_lshl_add_u64 v[54:55], v[130:131], 2, s[30:31]
	v_add_f32_e32 v132, v132, v133
	v_add_f32_e32 v64, v64, v65
	global_store_dwordx4 v[54:55], v[50:53], off sc1
	v_mul_f32_e32 v54, v51, v51
	v_mul_f32_e32 v55, v53, v53
	v_add_f32_e32 v64, v132, v64
	v_add_f32_e32 v60, v60, v61
	v_fmac_f32_e32 v54, v50, v50
	v_fmac_f32_e32 v55, v52, v52
	v_add_f32_e32 v60, v64, v60
	v_add_f32_e32 v54, v54, v55
	v_add_f32_e32 v54, v60, v54
	v_cvt_pk_bf16_f32 v50, v50, v51
	v_cvt_pk_bf16_f32 v51, v52, v53
	v_lshl_add_u64 v[52:53], v[130:131], 1, s[36:37]
	global_store_dwordx2 v[52:53], v[50:51], off
	ds_bpermute_b32 v50, v142, v54
	s_waitcnt lgkmcnt(0)
	v_add_f32_e32 v50, v54, v50
	ds_bpermute_b32 v51, v143, v50
	s_and_saveexec_b64 s[4:5], s[40:41]
	s_cbranch_execz .LBB0_1435
	v_lshlrev_b64 v[52:53], 7, v[128:129]
	v_lshl_add_u64 v[52:53], s[44:45], 0, v[52:53]
	v_lshl_add_u64 v[52:53], s[56:57], 2, v[52:53]
	s_lshl_b32 s10, s23, 2
	v_lshl_add_u64 v[52:53], v[52:53], 0, s[10:11]
	s_waitcnt lgkmcnt(0)
	v_add_f32_e32 v50, v50, v51
	global_store_dword v[52:53], v50, off
.LBB0_1435:
	s_or_b64 exec, exec, s[4:5]
	s_waitcnt lgkmcnt(0)
	v_lshlrev_b64 v[50:51], 11, v[126:127]
	v_lshl_add_u64 v[50:51], v[50:51], 0, v[196:197]
	s_waitcnt vmcnt(19)
	v_pk_add_f32 v[48:49], v[48:49], v[112:113]
	v_pk_add_f32 v[46:47], v[46:47], v[110:111]
	v_lshl_add_u64 v[52:53], v[50:51], 2, s[30:31]
	global_store_dwordx4 v[52:53], v[46:49], off sc1
	v_mul_f32_e32 v52, v47, v47
	v_mul_f32_e32 v53, v49, v49
	v_fmac_f32_e32 v52, v46, v46
	v_fmac_f32_e32 v53, v48, v48
	v_cvt_pk_bf16_f32 v46, v46, v47
	v_cvt_pk_bf16_f32 v47, v48, v49
	v_lshl_add_u64 v[48:49], v[50:51], 1, s[36:37]
	global_store_dwordx2 v[48:49], v[46:47], off
	v_or_b32_e32 v46, 16, v50
	v_mov_b32_e32 v47, v51
	s_waitcnt vmcnt(20)
	v_pk_add_f32 v[44:45], v[44:45], v[108:109]
	v_pk_add_f32 v[42:43], v[42:43], v[106:107]
	v_lshl_add_u64 v[48:49], v[46:47], 2, s[30:31]
	global_store_dwordx4 v[48:49], v[42:45], off sc1
	v_mul_f32_e32 v48, v43, v43
	v_mul_f32_e32 v49, v45, v45
	v_fmac_f32_e32 v48, v42, v42
	v_fmac_f32_e32 v49, v44, v44
	v_cvt_pk_bf16_f32 v42, v42, v43
	v_cvt_pk_bf16_f32 v43, v44, v45
	v_lshl_add_u64 v[44:45], v[46:47], 1, s[36:37]
	global_store_dwordx2 v[44:45], v[42:43], off
	v_or_b32_e32 v42, 0x80, v50
	v_mov_b32_e32 v43, v51
	s_waitcnt vmcnt(21)
	v_pk_add_f32 v[40:41], v[40:41], v[104:105]
	v_pk_add_f32 v[38:39], v[38:39], v[102:103]
	v_lshl_add_u64 v[44:45], v[42:43], 2, s[30:31]
	global_store_dwordx4 v[44:45], v[38:41], off sc1
	v_mul_f32_e32 v44, v39, v39
	v_mul_f32_e32 v45, v41, v41
	v_add_f32_e32 v52, v52, v53
	v_add_f32_e32 v48, v48, v49
	v_fmac_f32_e32 v44, v38, v38
	v_fmac_f32_e32 v45, v40, v40
	v_add_f32_e32 v48, v52, v48
	v_add_f32_e32 v44, v44, v45
	v_add_f32_e32 v46, v48, v44
	v_cvt_pk_bf16_f32 v44, v38, v39
	s_waitcnt vmcnt(21)
	v_pk_add_f32 v[38:39], v[36:37], v[100:101]
	v_pk_add_f32 v[36:37], v[34:35], v[98:99]
	v_mul_f32_e32 v35, v39, v39
	v_mul_f32_e32 v34, v37, v37
	v_fmac_f32_e32 v34, v36, v36
	v_fmac_f32_e32 v35, v38, v38
	v_add_f32_e32 v34, v34, v35
	v_cvt_pk_bf16_f32 v45, v40, v41
	v_lshl_add_u64 v[40:41], v[42:43], 1, s[36:37]
	v_add_f32_e32 v42, v46, v34
	ds_bpermute_b32 v43, v142, v42
	v_or_b32_e32 v50, 0x90, v50
	v_lshl_add_u64 v[34:35], v[50:51], 2, s[30:31]
	global_store_dwordx2 v[40:41], v[44:45], off
	global_store_dwordx4 v[34:35], v[36:39], off sc1
	s_waitcnt lgkmcnt(0)
	v_add_f32_e32 v34, v42, v43
	ds_bpermute_b32 v35, v143, v34
	v_cvt_pk_bf16_f32 v36, v36, v37
	v_cvt_pk_bf16_f32 v37, v38, v39
	v_lshl_add_u64 v[38:39], v[50:51], 1, s[36:37]
	global_store_dwordx2 v[38:39], v[36:37], off
	s_and_saveexec_b64 s[4:5], s[40:41]
	s_cbranch_execz .LBB0_1437
	v_lshlrev_b64 v[36:37], 7, v[126:127]
	v_lshl_add_u64 v[36:37], s[44:45], 0, v[36:37]
	v_lshl_add_u64 v[36:37], s[56:57], 2, v[36:37]
	s_lshl_b32 s10, s23, 2
	v_lshl_add_u64 v[36:37], v[36:37], 0, s[10:11]
	s_waitcnt lgkmcnt(0)
	v_add_f32_e32 v34, v34, v35
	global_store_dword v[36:37], v34, off
.LBB0_1437:
	s_or_b64 exec, exec, s[4:5]
	s_waitcnt lgkmcnt(0)
	v_lshlrev_b64 v[34:35], 11, v[124:125]
	v_lshl_add_u64 v[34:35], v[34:35], 0, v[196:197]
	s_waitcnt vmcnt(23)
	v_pk_add_f32 v[32:33], v[32:33], v[96:97]
	v_pk_add_f32 v[30:31], v[30:31], v[94:95]
	v_lshl_add_u64 v[36:37], v[34:35], 2, s[30:31]
	global_store_dwordx4 v[36:37], v[30:33], off sc1
	v_mul_f32_e32 v36, v31, v31
	v_mul_f32_e32 v37, v33, v33
	v_fmac_f32_e32 v36, v30, v30
	v_fmac_f32_e32 v37, v32, v32
	v_cvt_pk_bf16_f32 v30, v30, v31
	v_cvt_pk_bf16_f32 v31, v32, v33
	v_lshl_add_u64 v[32:33], v[34:35], 1, s[36:37]
	global_store_dwordx2 v[32:33], v[30:31], off
	v_or_b32_e32 v30, 16, v34
	v_mov_b32_e32 v31, v35
	s_waitcnt vmcnt(24)
	v_pk_add_f32 v[28:29], v[28:29], v[92:93]
	v_pk_add_f32 v[26:27], v[26:27], v[90:91]
	v_lshl_add_u64 v[32:33], v[30:31], 2, s[30:31]
	global_store_dwordx4 v[32:33], v[26:29], off sc1
	v_mul_f32_e32 v32, v27, v27
	v_mul_f32_e32 v33, v29, v29
	v_fmac_f32_e32 v32, v26, v26
	v_fmac_f32_e32 v33, v28, v28
	v_cvt_pk_bf16_f32 v26, v26, v27
	v_cvt_pk_bf16_f32 v27, v28, v29
	v_lshl_add_u64 v[28:29], v[30:31], 1, s[36:37]
	global_store_dwordx2 v[28:29], v[26:27], off
	v_or_b32_e32 v26, 0x80, v34
	v_mov_b32_e32 v27, v35
	s_waitcnt vmcnt(25)
	v_pk_add_f32 v[24:25], v[24:25], v[84:85]
	v_pk_add_f32 v[22:23], v[22:23], v[82:83]
	v_lshl_add_u64 v[28:29], v[26:27], 2, s[30:31]
	global_store_dwordx4 v[28:29], v[22:25], off sc1
	v_mul_f32_e32 v28, v23, v23
	v_mul_f32_e32 v29, v25, v25
	v_add_f32_e32 v36, v36, v37
	v_add_f32_e32 v32, v32, v33
	v_fmac_f32_e32 v28, v22, v22
	v_fmac_f32_e32 v29, v24, v24
	v_add_f32_e32 v32, v36, v32
	v_add_f32_e32 v28, v28, v29
	v_add_f32_e32 v30, v32, v28
	v_cvt_pk_bf16_f32 v28, v22, v23
	s_waitcnt vmcnt(25)
	v_pk_add_f32 v[22:23], v[20:21], v[76:77]
	v_pk_add_f32 v[20:21], v[18:19], v[74:75]
	v_mul_f32_e32 v19, v23, v23
	v_mul_f32_e32 v18, v21, v21
	v_fmac_f32_e32 v18, v20, v20
	v_fmac_f32_e32 v19, v22, v22
	v_add_f32_e32 v18, v18, v19
	v_cvt_pk_bf16_f32 v29, v24, v25
	v_lshl_add_u64 v[24:25], v[26:27], 1, s[36:37]
	v_add_f32_e32 v26, v30, v18
	ds_bpermute_b32 v27, v142, v26
	v_or_b32_e32 v34, 0x90, v34
	v_lshl_add_u64 v[18:19], v[34:35], 2, s[30:31]
	global_store_dwordx2 v[24:25], v[28:29], off
	global_store_dwordx4 v[18:19], v[20:23], off sc1
	s_waitcnt lgkmcnt(0)
	v_add_f32_e32 v18, v26, v27
	ds_bpermute_b32 v19, v143, v18
	v_cvt_pk_bf16_f32 v20, v20, v21
	v_cvt_pk_bf16_f32 v21, v22, v23
	v_lshl_add_u64 v[22:23], v[34:35], 1, s[36:37]
	global_store_dwordx2 v[22:23], v[20:21], off
	s_and_saveexec_b64 s[4:5], s[40:41]
	s_cbranch_execz .LBB0_1439
	v_lshlrev_b64 v[20:21], 7, v[124:125]
	v_lshl_add_u64 v[20:21], s[44:45], 0, v[20:21]
	v_lshl_add_u64 v[20:21], s[56:57], 2, v[20:21]
	s_lshl_b32 s10, s23, 2
	v_lshl_add_u64 v[20:21], v[20:21], 0, s[10:11]
	s_waitcnt lgkmcnt(0)
	v_add_f32_e32 v18, v18, v19
	global_store_dword v[20:21], v18, off
.LBB0_1439:
	s_or_b64 exec, exec, s[4:5]
	s_waitcnt lgkmcnt(0)
	v_lshlrev_b64 v[18:19], 11, v[122:123]
	v_lshl_add_u64 v[18:19], v[18:19], 0, v[196:197]
	s_waitcnt vmcnt(27)
	v_pk_add_f32 v[16:17], v[16:17], v[88:89]
	v_pk_add_f32 v[14:15], v[14:15], v[86:87]
	v_lshl_add_u64 v[20:21], v[18:19], 2, s[30:31]
	global_store_dwordx4 v[20:21], v[14:17], off sc1
	v_mul_f32_e32 v20, v15, v15
	v_mul_f32_e32 v21, v17, v17
	v_fmac_f32_e32 v20, v14, v14
	v_fmac_f32_e32 v21, v16, v16
	v_cvt_pk_bf16_f32 v14, v14, v15
	v_cvt_pk_bf16_f32 v15, v16, v17
	v_lshl_add_u64 v[16:17], v[18:19], 1, s[36:37]
	global_store_dwordx2 v[16:17], v[14:15], off
	v_or_b32_e32 v14, 16, v18
	v_mov_b32_e32 v15, v19
	s_waitcnt vmcnt(28)
	v_pk_add_f32 v[12:13], v[12:13], v[80:81]
	v_pk_add_f32 v[10:11], v[10:11], v[78:79]
	v_lshl_add_u64 v[16:17], v[14:15], 2, s[30:31]
	global_store_dwordx4 v[16:17], v[10:13], off sc1
	v_mul_f32_e32 v16, v11, v11
	v_mul_f32_e32 v17, v13, v13
	v_fmac_f32_e32 v16, v10, v10
	v_fmac_f32_e32 v17, v12, v12
	v_cvt_pk_bf16_f32 v10, v10, v11
	v_cvt_pk_bf16_f32 v11, v12, v13
	v_lshl_add_u64 v[12:13], v[14:15], 1, s[36:37]
	global_store_dwordx2 v[12:13], v[10:11], off
	v_or_b32_e32 v10, 0x80, v18
	v_mov_b32_e32 v11, v19
	s_waitcnt vmcnt(29)
	v_pk_add_f32 v[8:9], v[8:9], v[72:73]
	v_pk_add_f32 v[6:7], v[6:7], v[70:71]
	v_lshl_add_u64 v[12:13], v[10:11], 2, s[30:31]
	global_store_dwordx4 v[12:13], v[6:9], off sc1
	v_mul_f32_e32 v12, v7, v7
	v_mul_f32_e32 v13, v9, v9
	v_add_f32_e32 v20, v20, v21
	v_add_f32_e32 v16, v16, v17
	v_fmac_f32_e32 v12, v6, v6
	v_fmac_f32_e32 v13, v8, v8
	v_add_f32_e32 v16, v20, v16
	v_add_f32_e32 v12, v12, v13
	v_add_f32_e32 v14, v16, v12
	v_cvt_pk_bf16_f32 v12, v6, v7
	s_waitcnt vmcnt(29)
	v_pk_add_f32 v[6:7], v[4:5], v[68:69]
	v_pk_add_f32 v[4:5], v[2:3], v[66:67]
	v_mul_f32_e32 v3, v7, v7
	v_mul_f32_e32 v2, v5, v5
	v_fmac_f32_e32 v2, v4, v4
	v_fmac_f32_e32 v3, v6, v6
	v_add_f32_e32 v2, v2, v3
	v_cvt_pk_bf16_f32 v13, v8, v9
	v_lshl_add_u64 v[8:9], v[10:11], 1, s[36:37]
	v_add_f32_e32 v10, v14, v2
	ds_bpermute_b32 v11, v142, v10
	v_or_b32_e32 v18, 0x90, v18
	v_lshl_add_u64 v[2:3], v[18:19], 2, s[30:31]
	global_store_dwordx2 v[8:9], v[12:13], off
	global_store_dwordx4 v[2:3], v[4:7], off sc1
	s_waitcnt lgkmcnt(0)
	v_add_f32_e32 v2, v10, v11
	ds_bpermute_b32 v3, v143, v2
	v_cvt_pk_bf16_f32 v4, v4, v5
	v_cvt_pk_bf16_f32 v5, v6, v7
	v_lshl_add_u64 v[6:7], v[18:19], 1, s[36:37]
	global_store_dwordx2 v[6:7], v[4:5], off
	s_and_saveexec_b64 s[4:5], s[40:41]
	s_cbranch_execz .LBB0_1441
	v_lshlrev_b64 v[4:5], 7, v[122:123]
	v_lshl_add_u64 v[4:5], s[44:45], 0, v[4:5]
	v_lshl_add_u64 v[4:5], s[56:57], 2, v[4:5]
	s_lshl_b32 s10, s23, 2
	v_lshl_add_u64 v[4:5], v[4:5], 0, s[10:11]
	s_waitcnt lgkmcnt(0)
	v_add_f32_e32 v2, v2, v3
	global_store_dword v[4:5], v2, off
